# comp-0 softmax in two half-tile passes (second under PV MFMAs), P1 packed in place, plus queue grouping
# speedup vs baseline: 1.0091x; 1.0091x over previous
; DI void attn_item(const Params& p, char* smem, u16* qbase, const u16* gabase, const u16* kbase, const u16* vtbase,
;                   int tkv, int nkt, int mylimit, const float* lam_p, const int g_wave) {
;     ...
;     if (kt < mylimit) {
;       const char* Kt = Kb + (kt & 1) * KBUF;
;       const char* Vt = Vb + (kt & 1) * VBUF;
;       int zq = 0, kz = (r & 15) * 16, vz = ((r >> 1) & 7) * 16;
;       asm volatile("" : "+v"(zq), "+v"(kz), "+v"(vz));
;       const char* Qk = Qs + zq;
;       bf16x8 pf0[4], pf1[4];
;       SOFTMAX_COMP(0, l0, m0, O0, pf0);
;       __builtin_amdgcn_sched_barrier(0);
;       SOFTMAX_COMP(1, l1, m1, O1, pf1);
.LBB0_711:
	s_cmp_ge_u32 s55, s78
	s_cbranch_scc1 .LBB0_717
	s_and_b32 s55, s50, 0x4000
	v_add_u32_e32 v16, s55, v198
	v_add_u32_e32 v216, v199, v16
	ds_read_b128 v[220:223], v216
	ds_read_b128 v[224:227], v216 offset:8192
	ds_read_b128 v[228:231], v205
	v_xad_u32 v217, v199, 32, v16
	ds_read_b128 v[232:235], v217
	ds_read_b128 v[236:239], v217 offset:8192
	ds_read_b128 v[240:243], v205 offset:32
	v_xad_u32 v216, v199, 64, v16
	ds_read_b128 v[244:247], v216
	ds_read_b128 v[248:251], v216 offset:8192
	ds_read_b128 v[200:203], v205 offset:64
	v_xad_u32 v217, v199, s79, v16
	ds_read_b128 v[208:211], v217
	ds_read_b128 v[212:215], v217 offset:8192
	s_waitcnt lgkmcnt(8)
	v_mfma_f32_32x32x16_bf16 v[162:177], v[220:223], v[228:231], 0
	v_mfma_f32_32x32x16_bf16 v[146:161], v[224:227], v[228:231], 0
	ds_read_b128 v[220:223], v205 offset:96
	s_waitcnt lgkmcnt(6)
	v_mfma_f32_32x32x16_bf16 v[162:177], v[232:235], v[240:243], v[162:177]
	v_mfma_f32_32x32x16_bf16 v[146:161], v[236:239], v[240:243], v[146:161]
	s_waitcnt lgkmcnt(3)
	v_mfma_f32_32x32x16_bf16 v[162:177], v[244:247], v[200:203], v[162:177]
	v_mfma_f32_32x32x16_bf16 v[146:161], v[248:251], v[200:203], v[146:161]
	s_waitcnt lgkmcnt(0)
	v_mfma_f32_32x32x16_bf16 v[162:177], v[208:211], v[220:223], v[162:177]
	v_mfma_f32_32x32x16_bf16 v[146:161], v[212:215], v[220:223], v[146:161]
	v_xad_u32 v254, v199, s80, v16
	ds_read_b128 v[200:203], v254
	ds_read_b128 v[208:211], v254 offset:8192
	ds_read_b128 v[212:215], v205 offset:128
	s_nop 7
	v_fma_f32 v216, v162, s97, -v207
	v_fma_f32 v217, v163, s97, -v207
	v_fma_f32 v252, v164, s97, -v207
	v_fma_f32 v253, v165, s97, -v207
	v_exp_f32_e32 v216, v216
	v_exp_f32_e32 v217, v217
	v_exp_f32_e32 v252, v252
	v_exp_f32_e32 v253, v253
	v_mov_b32_e32 v17, v216
	v_mov_b32_e32 v219, v217
	v_cvt_pk_bf16_f32 v178, v216, v217
	v_cvt_pk_bf16_f32 v179, v252, v253
	v_add_f32_e32 v17, v252, v17
	v_add_f32_e32 v219, v253, v219
	s_waitcnt lgkmcnt(0)
	v_mfma_f32_32x32x16_bf16 v[220:235], v[200:203], v[212:215], 0
	v_mfma_f32_32x32x16_bf16 v[236:251], v[208:211], v[212:215], 0
	v_xad_u32 v204, v199, s81, v16
	ds_read_b128 v[200:203], v204
	ds_read_b128 v[208:211], v204 offset:8192
	ds_read_b128 v[212:215], v205 offset:160
	v_fma_f32 v216, v166, s97, -v207
	v_fma_f32 v217, v167, s97, -v207
	v_fma_f32 v252, v168, s97, -v207
	v_fma_f32 v253, v169, s97, -v207
	v_exp_f32_e32 v216, v216
	v_exp_f32_e32 v217, v217
	v_exp_f32_e32 v252, v252
	v_exp_f32_e32 v253, v253
	v_add_f32_e32 v17, v216, v17
	v_add_f32_e32 v219, v217, v219
	v_cvt_pk_bf16_f32 v180, v216, v217
	v_cvt_pk_bf16_f32 v181, v252, v253
	v_add_f32_e32 v17, v252, v17
	v_add_f32_e32 v219, v253, v219
	s_waitcnt lgkmcnt(0)
	v_mfma_f32_32x32x16_bf16 v[220:235], v[200:203], v[212:215], v[220:235]
	v_mfma_f32_32x32x16_bf16 v[236:251], v[208:211], v[212:215], v[236:251]
	v_xad_u32 v254, v199, s82, v16
	ds_read_b128 v[200:203], v254
	ds_read_b128 v[208:211], v254 offset:8192
	ds_read_b128 v[212:215], v205 offset:192
	v_fma_f32 v216, v170, s97, -v207
	v_fma_f32 v217, v171, s97, -v207
	v_fma_f32 v252, v172, s97, -v207
	v_fma_f32 v253, v173, s97, -v207
	v_exp_f32_e32 v216, v216
	v_exp_f32_e32 v217, v217
	v_exp_f32_e32 v252, v252
	v_exp_f32_e32 v253, v253
	v_add_f32_e32 v17, v216, v17
	v_add_f32_e32 v219, v217, v219
	v_cvt_pk_bf16_f32 v12, v216, v217
	v_cvt_pk_bf16_f32 v13, v252, v253
	v_add_f32_e32 v17, v252, v17
	v_add_f32_e32 v219, v253, v219
	s_waitcnt lgkmcnt(0)
	v_mfma_f32_32x32x16_bf16 v[220:235], v[200:203], v[212:215], v[220:235]
	v_mfma_f32_32x32x16_bf16 v[236:251], v[208:211], v[212:215], v[236:251]
	v_xad_u32 v204, v199, s83, v16
	ds_read_b128 v[200:203], v204
	ds_read_b128 v[208:211], v204 offset:8192
	ds_read_b128 v[212:215], v205 offset:224
	v_fma_f32 v216, v174, s97, -v207
	v_fma_f32 v217, v175, s97, -v207
	v_fma_f32 v252, v176, s97, -v207
	v_fma_f32 v253, v177, s97, -v207
	v_exp_f32_e32 v216, v216
	v_exp_f32_e32 v217, v217
	v_exp_f32_e32 v252, v252
	v_exp_f32_e32 v253, v253
	v_add_f32_e32 v17, v216, v17
	v_add_f32_e32 v219, v217, v219
	v_cvt_pk_bf16_f32 v14, v216, v217
	v_cvt_pk_bf16_f32 v15, v252, v253
	v_add_f32_e32 v17, v252, v17
	v_add_f32_e32 v219, v253, v219
	s_waitcnt lgkmcnt(0)
	v_mfma_f32_32x32x16_bf16 v[220:235], v[200:203], v[212:215], v[220:235]
	v_mfma_f32_32x32x16_bf16 v[236:251], v[208:211], v[212:215], v[236:251]
	v_add_f32_e32 v17, v17, v219
	v_cmp_lt_f32_e32 vcc, 0x43800000, v17
	s_cmp_lg_u64 vcc, 0
	s_cbranch_scc0 .Lat_ok0a
	v_max3_f32 v17, v162, v163, v164
	v_max3_f32 v17, v17, v165, v166
	v_max3_f32 v17, v17, v167, v168
	v_max3_f32 v17, v17, v169, v170
	v_max3_f32 v17, v17, v171, v172
	v_max3_f32 v17, v17, v173, v174
	v_max3_f32 v17, v17, v175, v176
	v_max_f32_e32 v17, v17, v177
	v_mov_b32_e32 v219, v17
	s_nop 1
	v_permlane32_swap_b32_e32 v17, v219
	v_max_f32_e32 v17, v17, v219
	v_mul_f32_e32 v17, s97, v17
	v_max_f32_e32 v219, v207, v17
	v_sub_f32_e32 v216, v207, v219
	v_exp_f32_e32 v216, v216
	v_mov_b32_e32 v207, v219
	s_nop 0
	v_pk_mul_f32 v[144:145], v[144:145], v[216:217] op_sel_hi:[1,0]
	v_pk_mul_f32 v[142:143], v[142:143], v[216:217] op_sel_hi:[1,0]
	v_pk_mul_f32 v[140:141], v[140:141], v[216:217] op_sel_hi:[1,0]
	v_pk_mul_f32 v[138:139], v[138:139], v[216:217] op_sel_hi:[1,0]
	v_pk_mul_f32 v[136:137], v[136:137], v[216:217] op_sel_hi:[1,0]
	v_pk_mul_f32 v[134:135], v[134:135], v[216:217] op_sel_hi:[1,0]
	v_pk_mul_f32 v[132:133], v[132:133], v[216:217] op_sel_hi:[1,0]
	v_pk_mul_f32 v[130:131], v[130:131], v[216:217] op_sel_hi:[1,0]
	v_pk_mul_f32 v[112:113], v[112:113], v[216:217] op_sel_hi:[1,0]
	v_pk_mul_f32 v[110:111], v[110:111], v[216:217] op_sel_hi:[1,0]
	v_pk_mul_f32 v[108:109], v[108:109], v[216:217] op_sel_hi:[1,0]
	v_pk_mul_f32 v[106:107], v[106:107], v[216:217] op_sel_hi:[1,0]
	v_pk_mul_f32 v[104:105], v[104:105], v[216:217] op_sel_hi:[1,0]
	v_pk_mul_f32 v[102:103], v[102:103], v[216:217] op_sel_hi:[1,0]
	v_pk_mul_f32 v[100:101], v[100:101], v[216:217] op_sel_hi:[1,0]
	v_pk_mul_f32 v[98:99], v[98:99], v[216:217] op_sel_hi:[1,0]
	v_pk_mul_f32 v[80:81], v[80:81], v[216:217] op_sel_hi:[1,0]
	v_pk_mul_f32 v[78:79], v[78:79], v[216:217] op_sel_hi:[1,0]
	v_pk_mul_f32 v[76:77], v[76:77], v[216:217] op_sel_hi:[1,0]
	v_pk_mul_f32 v[74:75], v[74:75], v[216:217] op_sel_hi:[1,0]
	v_pk_mul_f32 v[72:73], v[72:73], v[216:217] op_sel_hi:[1,0]
	v_pk_mul_f32 v[70:71], v[70:71], v[216:217] op_sel_hi:[1,0]
	v_pk_mul_f32 v[68:69], v[68:69], v[216:217] op_sel_hi:[1,0]
	v_pk_mul_f32 v[66:67], v[66:67], v[216:217] op_sel_hi:[1,0]
	v_pk_mul_f32 v[48:49], v[48:49], v[216:217] op_sel_hi:[1,0]
	v_pk_mul_f32 v[46:47], v[46:47], v[216:217] op_sel_hi:[1,0]
	v_pk_mul_f32 v[44:45], v[44:45], v[216:217] op_sel_hi:[1,0]
	v_pk_mul_f32 v[42:43], v[42:43], v[216:217] op_sel_hi:[1,0]
	v_pk_mul_f32 v[40:41], v[40:41], v[216:217] op_sel_hi:[1,0]
	v_pk_mul_f32 v[38:39], v[38:39], v[216:217] op_sel_hi:[1,0]
	v_pk_mul_f32 v[36:37], v[36:37], v[216:217] op_sel_hi:[1,0]
	v_pk_mul_f32 v[34:35], v[34:35], v[216:217] op_sel_hi:[1,0]
	v_mul_f32_e32 v186, v186, v216
	v_fma_f32 v216, v162, s97, -v207
	v_fma_f32 v217, v163, s97, -v207
	v_fma_f32 v252, v164, s97, -v207
	v_fma_f32 v253, v165, s97, -v207
	v_exp_f32_e32 v216, v216
	v_exp_f32_e32 v217, v217
	v_exp_f32_e32 v252, v252
	v_exp_f32_e32 v253, v253
	v_mov_b32_e32 v17, v216
	v_mov_b32_e32 v219, v217
	v_cvt_pk_bf16_f32 v178, v216, v217
	v_cvt_pk_bf16_f32 v179, v252, v253
	v_add_f32_e32 v17, v252, v17
	v_add_f32_e32 v219, v253, v219
	v_fma_f32 v216, v166, s97, -v207
	v_fma_f32 v217, v167, s97, -v207
	v_fma_f32 v252, v168, s97, -v207
	v_fma_f32 v253, v169, s97, -v207
	v_exp_f32_e32 v216, v216
	v_exp_f32_e32 v217, v217
	v_exp_f32_e32 v252, v252
	v_exp_f32_e32 v253, v253
	v_add_f32_e32 v17, v216, v17
	v_add_f32_e32 v219, v217, v219
	v_cvt_pk_bf16_f32 v180, v216, v217
	v_cvt_pk_bf16_f32 v181, v252, v253
	v_add_f32_e32 v17, v252, v17
	v_add_f32_e32 v219, v253, v219
	v_fma_f32 v216, v170, s97, -v207
	v_fma_f32 v217, v171, s97, -v207
	v_fma_f32 v252, v172, s97, -v207
	v_fma_f32 v253, v173, s97, -v207
	v_exp_f32_e32 v216, v216
	v_exp_f32_e32 v217, v217
	v_exp_f32_e32 v252, v252
	v_exp_f32_e32 v253, v253
	v_add_f32_e32 v17, v216, v17
	v_add_f32_e32 v219, v217, v219
	v_cvt_pk_bf16_f32 v12, v216, v217
	v_cvt_pk_bf16_f32 v13, v252, v253
	v_add_f32_e32 v17, v252, v17
	v_add_f32_e32 v219, v253, v219
	v_fma_f32 v216, v174, s97, -v207
	v_fma_f32 v217, v175, s97, -v207
	v_fma_f32 v252, v176, s97, -v207
	v_fma_f32 v253, v177, s97, -v207
	v_exp_f32_e32 v216, v216
	v_exp_f32_e32 v217, v217
	v_exp_f32_e32 v252, v252
	v_exp_f32_e32 v253, v253
	v_add_f32_e32 v17, v216, v17
	v_add_f32_e32 v219, v217, v219
	v_cvt_pk_bf16_f32 v14, v216, v217
	v_cvt_pk_bf16_f32 v15, v252, v253
	v_add_f32_e32 v17, v252, v17
	v_add_f32_e32 v219, v253, v219
	v_add_f32_e32 v17, v17, v219

; DI void attn_item(const Params& p, char* smem, u16* qbase, const u16* gabase, const u16* kbase, const u16* vtbase,
;                   int tkv, int nkt, int mylimit, const float* lam_p, const int g_wave) {
;     ...
; #pragma unroll
;       for (int d = 0; d < 4; ++d) {
;         const int vrow = 32 * d + r;
; #pragma unroll
;         for (int sp = 0; sp < 4; ++sp) {
;           const u32x2 lo = *(const u32x2*)(Vt + vrow * 128 + ((32 * sp) ^ vz) + 8 * hh);
;           const u32x2 hi = *(const u32x2*)(Vt + vrow * 128 + ((32 * sp + 16) ^ vz) + 8 * hh);
;           u32x4 w = {lo[0], lo[1], hi[0], hi[1]};
;           const bf16x8 vf = *reinterpret_cast<bf16x8*>(&w);
;           O0[d] = __builtin_amdgcn_mfma_f32_32x32x16_bf16(vf, pf0[sp], O0[d], 0, 0, 0);
;           O1[d] = __builtin_amdgcn_mfma_f32_32x32x16_bf16(vf, pf1[sp], O1[d], 0, 0, 0);
;         }
.Lat_nr1:
	s_waitcnt lgkmcnt(1)
	v_mfma_f32_32x32x16_bf16 v[66:81], v[170:173], v[178:181], v[66:81]
	v_fma_f32 v220, v220, s97, -v2
	v_fma_f32 v221, v221, s97, -v2
	v_fma_f32 v222, v222, s97, -v2
	v_fma_f32 v223, v223, s97, -v2
	v_fma_f32 v224, v224, s97, -v2
	v_fma_f32 v225, v225, s97, -v2
	v_fma_f32 v226, v226, s97, -v2
	v_fma_f32 v227, v227, s97, -v2
	s_waitcnt lgkmcnt(0)
	v_mfma_f32_32x32x16_bf16 v[34:49], v[174:177], v[178:181], v[34:49]
	v_exp_f32_e32 v220, v220
	v_exp_f32_e32 v221, v221
	v_exp_f32_e32 v222, v222
	v_exp_f32_e32 v223, v223
	v_exp_f32_e32 v224, v224
	v_exp_f32_e32 v225, v225
	v_exp_f32_e32 v226, v226
	v_exp_f32_e32 v227, v227
	v_mov_b32_e32 v17, v220
	v_mov_b32_e32 v219, v221
	v_add_f32_e32 v17, v222, v17
	v_add_f32_e32 v219, v223, v219
	v_add_f32_e32 v17, v224, v17
	v_add_f32_e32 v219, v225, v219
	v_add_f32_e32 v17, v226, v17
	v_add_f32_e32 v219, v227, v219
	v_cvt_pk_bf16_f32 v220, v220, v221
	v_cvt_pk_bf16_f32 v221, v222, v223
	v_cvt_pk_bf16_f32 v222, v224, v225
	v_cvt_pk_bf16_f32 v223, v226, v227
	s_nop 1
	v_mfma_f32_32x32x16_bf16 v[114:129], v[162:165], v[220:223], v[114:129]
	ds_read_b128 v[162:165], v201 offset:32768
	v_fma_f32 v228, v228, s97, -v2
	v_fma_f32 v229, v229, s97, -v2
	v_fma_f32 v230, v230, s97, -v2
	v_fma_f32 v231, v231, s97, -v2
	v_fma_f32 v232, v232, s97, -v2
	v_fma_f32 v233, v233, s97, -v2
	v_fma_f32 v234, v234, s97, -v2
	v_mfma_f32_32x32x16_bf16 v[82:97], v[166:169], v[220:223], v[82:97]
	ds_read_b128 v[166:169], v201 offset:36864
	v_fma_f32 v235, v235, s97, -v2
	v_exp_f32_e32 v228, v228
	v_exp_f32_e32 v229, v229
	v_exp_f32_e32 v230, v230
	v_exp_f32_e32 v231, v231
	v_exp_f32_e32 v232, v232
	v_exp_f32_e32 v233, v233
	v_mfma_f32_32x32x16_bf16 v[50:65], v[170:173], v[220:223], v[50:65]
	ds_read_b128 v[170:173], v201 offset:40960
	v_exp_f32_e32 v234, v234
	v_exp_f32_e32 v235, v235
	v_add_f32_e32 v17, v228, v17
	v_add_f32_e32 v219, v229, v219
	v_add_f32_e32 v17, v230, v17
	v_add_f32_e32 v219, v231, v219
	v_add_f32_e32 v17, v232, v17
	v_mfma_f32_32x32x16_bf16 v[18:33], v[174:177], v[220:223], v[18:33]
	ds_read_b128 v[174:177], v201 offset:45056
	v_add_f32_e32 v219, v233, v219
	v_add_f32_e32 v17, v234, v17
	v_add_f32_e32 v219, v235, v219
	v_cvt_pk_bf16_f32 v228, v228, v229
	v_cvt_pk_bf16_f32 v229, v230, v231
	v_cvt_pk_bf16_f32 v230, v232, v233
	v_cvt_pk_bf16_f32 v231, v234, v235
	s_waitcnt lgkmcnt(3)
	v_mfma_f32_32x32x16_bf16 v[130:145], v[162:165], v[12:15], v[130:145]
	v_fma_f32 v236, v236, s97, -v2
	v_fma_f32 v237, v237, s97, -v2
	v_fma_f32 v238, v238, s97, -v2
	v_fma_f32 v239, v239, s97, -v2
	v_mfma_f32_32x32x16_bf16 v[114:129], v[162:165], v[228:231], v[114:129]
	ds_read_b128 v[162:165], v202 offset:32768
	v_fma_f32 v240, v240, s97, -v2
	v_fma_f32 v241, v241, s97, -v2
	v_fma_f32 v242, v242, s97, -v2
	v_fma_f32 v243, v243, s97, -v2
	s_waitcnt lgkmcnt(3)
	v_mfma_f32_32x32x16_bf16 v[98:113], v[166:169], v[12:15], v[98:113]
	v_exp_f32_e32 v236, v236
	v_exp_f32_e32 v237, v237
	v_exp_f32_e32 v238, v238
	v_exp_f32_e32 v239, v239
	v_mfma_f32_32x32x16_bf16 v[82:97], v[166:169], v[228:231], v[82:97]
	ds_read_b128 v[166:169], v202 offset:36864
	v_exp_f32_e32 v240, v240
	v_exp_f32_e32 v241, v241
	v_exp_f32_e32 v242, v242
	v_exp_f32_e32 v243, v243
	s_waitcnt lgkmcnt(3)
	v_mfma_f32_32x32x16_bf16 v[66:81], v[170:173], v[12:15], v[66:81]
	v_add_f32_e32 v17, v236, v17
	v_add_f32_e32 v219, v237, v219
	v_add_f32_e32 v17, v238, v17
	v_add_f32_e32 v219, v239, v219
	v_mfma_f32_32x32x16_bf16 v[50:65], v[170:173], v[228:231], v[50:65]
	ds_read_b128 v[170:173], v202 offset:40960
	v_add_f32_e32 v17, v240, v17
	v_add_f32_e32 v219, v241, v219
	v_add_f32_e32 v17, v242, v17
	v_add_f32_e32 v219, v243, v219
	s_waitcnt lgkmcnt(3)
	v_mfma_f32_32x32x16_bf16 v[34:49], v[174:177], v[12:15], v[34:49]
	v_cvt_pk_bf16_f32 v236, v236, v237
	v_cvt_pk_bf16_f32 v237, v238, v239
	v_cvt_pk_bf16_f32 v238, v240, v241
	v_cvt_pk_bf16_f32 v239, v242, v243
	v_mfma_f32_32x32x16_bf16 v[18:33], v[174:177], v[228:231], v[18:33]
	ds_read_b128 v[174:177], v202 offset:45056
	s_waitcnt lgkmcnt(3)
	v_mfma_f32_32x32x16_bf16 v[114:129], v[162:165], v[236:239], v[114:129]
	v_fma_f32 v216, v146, s97, -v207
	v_fma_f32 v217, v147, s97, -v207
	v_fma_f32 v252, v148, s97, -v207
	v_fma_f32 v253, v149, s97, -v207
	v_exp_f32_e32 v216, v216
	v_exp_f32_e32 v217, v217
	v_exp_f32_e32 v252, v252
	v_exp_f32_e32 v253, v253
	v_mov_b32_e32 v254, v216
	v_mov_b32_e32 v204, v217
	v_cvt_pk_bf16_f32 v8, v216, v217
	v_cvt_pk_bf16_f32 v9, v252, v253
	v_add_f32_e32 v254, v252, v254
	v_add_f32_e32 v204, v253, v204
	s_waitcnt lgkmcnt(2)
	v_mfma_f32_32x32x16_bf16 v[82:97], v[166:169], v[236:239], v[82:97]
	v_fma_f32 v216, v150, s97, -v207
	v_fma_f32 v217, v151, s97, -v207
	v_fma_f32 v252, v152, s97, -v207
	v_fma_f32 v253, v153, s97, -v207
	v_exp_f32_e32 v216, v216
	v_exp_f32_e32 v217, v217
	v_exp_f32_e32 v252, v252
	v_exp_f32_e32 v253, v253
	v_add_f32_e32 v254, v216, v254
	v_add_f32_e32 v204, v217, v204
	v_cvt_pk_bf16_f32 v10, v216, v217
	v_cvt_pk_bf16_f32 v11, v252, v253
	v_add_f32_e32 v254, v252, v254
	v_add_f32_e32 v204, v253, v204
	s_waitcnt lgkmcnt(1)
	v_mfma_f32_32x32x16_bf16 v[50:65], v[170:173], v[236:239], v[50:65]
	v_fma_f32 v216, v154, s97, -v207
	v_fma_f32 v217, v155, s97, -v207
	v_fma_f32 v252, v156, s97, -v207
	v_fma_f32 v253, v157, s97, -v207
	v_exp_f32_e32 v216, v216
	v_exp_f32_e32 v217, v217
	v_exp_f32_e32 v252, v252
	v_exp_f32_e32 v253, v253
	v_add_f32_e32 v254, v216, v254
	v_add_f32_e32 v204, v217, v204
	v_cvt_pk_bf16_f32 v4, v216, v217
	v_cvt_pk_bf16_f32 v5, v252, v253
	v_add_f32_e32 v254, v252, v254
	v_add_f32_e32 v204, v253, v204
	s_waitcnt lgkmcnt(0)
	v_mfma_f32_32x32x16_bf16 v[18:33], v[174:177], v[236:239], v[18:33]
	v_fma_f32 v216, v158, s97, -v207
	v_fma_f32 v217, v159, s97, -v207
	v_fma_f32 v252, v160, s97, -v207
	v_fma_f32 v253, v161, s97, -v207
	v_exp_f32_e32 v216, v216
	v_exp_f32_e32 v217, v217
	v_exp_f32_e32 v252, v252
	v_exp_f32_e32 v253, v253
	v_add_f32_e32 v254, v216, v254
	v_add_f32_e32 v204, v217, v204
	v_cvt_pk_bf16_f32 v6, v216, v217
	v_cvt_pk_bf16_f32 v7, v252, v253
	v_add_f32_e32 v254, v252, v254
	v_add_f32_e32 v204, v253, v204
	v_add_f32_e32 v254, v254, v204
	v_cmp_lt_f32_e32 vcc, 0x43800000, v254
	s_cmp_lg_u64 vcc, 0
	s_cbranch_scc0 .Lat_ok0b
; DI void attn_item(const Params& p, char* smem, u16* qbase, const u16* gabase, const u16* kbase, const u16* vtbase,
;                   int tkv, int nkt, int mylimit, const float* lam_p, const int g_wave) {
;     ...
; #pragma unroll
;       for (int d = 0; d < 4; ++d) {
;         const int vrow = 32 * d + r;
; #pragma unroll
;         for (int sp = 0; sp < 4; ++sp) {
;           const u32x2 lo = *(const u32x2*)(Vt + vrow * 128 + ((32 * sp) ^ vz) + 8 * hh);
;           const u32x2 hi = *(const u32x2*)(Vt + vrow * 128 + ((32 * sp + 16) ^ vz) + 8 * hh);
;           u32x4 w = {lo[0], lo[1], hi[0], hi[1]};
;           const bf16x8 vf = *reinterpret_cast<bf16x8*>(&w);
;           O0[d] = __builtin_amdgcn_mfma_f32_32x32x16_bf16(vf, pf0[sp], O0[d], 0, 0, 0);
;           O1[d] = __builtin_amdgcn_mfma_f32_32x32x16_bf16(vf, pf1[sp], O1[d], 0, 0, 0);
;         }
	s_nop 15
	s_nop 15
	v_max3_f32 v254, v146, v147, v148
	v_max3_f32 v254, v254, v149, v150
	v_max3_f32 v254, v254, v151, v152
	v_max3_f32 v254, v254, v153, v154
	v_max3_f32 v254, v254, v155, v156
	v_max3_f32 v254, v254, v157, v158
	v_max3_f32 v254, v254, v159, v160
	v_max_f32_e32 v254, v254, v161
	v_mov_b32_e32 v204, v254
	s_nop 1
	v_permlane32_swap_b32_e32 v254, v204
	v_max_f32_e32 v254, v254, v204
	v_mul_f32_e32 v254, s97, v254
	v_max_f32_e32 v204, v207, v254
	v_sub_f32_e32 v216, v207, v204
	v_exp_f32_e32 v216, v216
	v_mov_b32_e32 v207, v204
	s_nop 0
	v_pk_mul_f32 v[144:145], v[144:145], v[216:217] op_sel_hi:[1,0]
	v_pk_mul_f32 v[142:143], v[142:143], v[216:217] op_sel_hi:[1,0]
	v_pk_mul_f32 v[140:141], v[140:141], v[216:217] op_sel_hi:[1,0]
	v_pk_mul_f32 v[138:139], v[138:139], v[216:217] op_sel_hi:[1,0]
	v_pk_mul_f32 v[136:137], v[136:137], v[216:217] op_sel_hi:[1,0]
	v_pk_mul_f32 v[134:135], v[134:135], v[216:217] op_sel_hi:[1,0]
	v_pk_mul_f32 v[132:133], v[132:133], v[216:217] op_sel_hi:[1,0]
	v_pk_mul_f32 v[130:131], v[130:131], v[216:217] op_sel_hi:[1,0]
	v_pk_mul_f32 v[112:113], v[112:113], v[216:217] op_sel_hi:[1,0]
	v_pk_mul_f32 v[110:111], v[110:111], v[216:217] op_sel_hi:[1,0]
	v_pk_mul_f32 v[108:109], v[108:109], v[216:217] op_sel_hi:[1,0]
	v_pk_mul_f32 v[106:107], v[106:107], v[216:217] op_sel_hi:[1,0]
	v_pk_mul_f32 v[104:105], v[104:105], v[216:217] op_sel_hi:[1,0]
	v_pk_mul_f32 v[102:103], v[102:103], v[216:217] op_sel_hi:[1,0]
	v_pk_mul_f32 v[100:101], v[100:101], v[216:217] op_sel_hi:[1,0]
	v_pk_mul_f32 v[98:99], v[98:99], v[216:217] op_sel_hi:[1,0]
	v_pk_mul_f32 v[80:81], v[80:81], v[216:217] op_sel_hi:[1,0]
	v_pk_mul_f32 v[78:79], v[78:79], v[216:217] op_sel_hi:[1,0]
	v_pk_mul_f32 v[76:77], v[76:77], v[216:217] op_sel_hi:[1,0]
	v_pk_mul_f32 v[74:75], v[74:75], v[216:217] op_sel_hi:[1,0]
	v_pk_mul_f32 v[72:73], v[72:73], v[216:217] op_sel_hi:[1,0]
	v_pk_mul_f32 v[70:71], v[70:71], v[216:217] op_sel_hi:[1,0]
	v_pk_mul_f32 v[68:69], v[68:69], v[216:217] op_sel_hi:[1,0]
	v_pk_mul_f32 v[66:67], v[66:67], v[216:217] op_sel_hi:[1,0]
	v_pk_mul_f32 v[48:49], v[48:49], v[216:217] op_sel_hi:[1,0]
	v_pk_mul_f32 v[46:47], v[46:47], v[216:217] op_sel_hi:[1,0]
	v_pk_mul_f32 v[44:45], v[44:45], v[216:217] op_sel_hi:[1,0]
	v_pk_mul_f32 v[42:43], v[42:43], v[216:217] op_sel_hi:[1,0]
	v_pk_mul_f32 v[40:41], v[40:41], v[216:217] op_sel_hi:[1,0]
	v_pk_mul_f32 v[38:39], v[38:39], v[216:217] op_sel_hi:[1,0]
	v_pk_mul_f32 v[36:37], v[36:37], v[216:217] op_sel_hi:[1,0]
	v_pk_mul_f32 v[34:35], v[34:35], v[216:217] op_sel_hi:[1,0]
	v_mul_f32_e32 v186, v186, v216
	v_fma_f32 v216, v146, s97, -v207
	v_fma_f32 v217, v147, s97, -v207
	v_fma_f32 v252, v148, s97, -v207
	v_fma_f32 v253, v149, s97, -v207
	v_exp_f32_e32 v216, v216
	v_exp_f32_e32 v217, v217
	v_exp_f32_e32 v252, v252
	v_exp_f32_e32 v253, v253
	v_mov_b32_e32 v254, v216
	v_mov_b32_e32 v204, v217
	v_cvt_pk_bf16_f32 v8, v216, v217
	v_cvt_pk_bf16_f32 v9, v252, v253
	v_add_f32_e32 v254, v252, v254
	v_add_f32_e32 v204, v253, v204
	v_fma_f32 v216, v150, s97, -v207
	v_fma_f32 v217, v151, s97, -v207
	v_fma_f32 v252, v152, s97, -v207
	v_fma_f32 v253, v153, s97, -v207
	v_exp_f32_e32 v216, v216
	v_exp_f32_e32 v217, v217
	v_exp_f32_e32 v252, v252
	v_exp_f32_e32 v253, v253
	v_add_f32_e32 v254, v216, v254
	v_add_f32_e32 v204, v217, v204
	v_cvt_pk_bf16_f32 v10, v216, v217
	v_cvt_pk_bf16_f32 v11, v252, v253
	v_add_f32_e32 v254, v252, v254
	v_add_f32_e32 v204, v253, v204
	v_fma_f32 v216, v154, s97, -v207
	v_fma_f32 v217, v155, s97, -v207
	v_fma_f32 v252, v156, s97, -v207
	v_fma_f32 v253, v157, s97, -v207
	v_exp_f32_e32 v216, v216
	v_exp_f32_e32 v217, v217
	v_exp_f32_e32 v252, v252
	v_exp_f32_e32 v253, v253
	v_add_f32_e32 v254, v216, v254
	v_add_f32_e32 v204, v217, v204
	v_cvt_pk_bf16_f32 v4, v216, v217
	v_cvt_pk_bf16_f32 v5, v252, v253
	v_add_f32_e32 v254, v252, v254
	v_add_f32_e32 v204, v253, v204
	v_fma_f32 v216, v158, s97, -v207
	v_fma_f32 v217, v159, s97, -v207
	v_fma_f32 v252, v160, s97, -v207
	v_fma_f32 v253, v161, s97, -v207
	v_exp_f32_e32 v216, v216
	v_exp_f32_e32 v217, v217
	v_exp_f32_e32 v252, v252
	v_exp_f32_e32 v253, v253
	v_add_f32_e32 v254, v216, v254
	v_add_f32_e32 v204, v217, v204
	v_cvt_pk_bf16_f32 v6, v216, v217
	v_cvt_pk_bf16_f32 v7, v252, v253
	v_add_f32_e32 v254, v252, v254
	v_add_f32_e32 v204, v253, v204
	v_add_f32_e32 v254, v254, v204
.Lat_ok0b:
	v_add_f32_e32 v186, v186, v254
	v_mfma_f32_32x32x16_bf16 v[130:145], v[162:165], v[8:11], v[130:145]
	ds_read_b128 v[162:165], v203 offset:32768
	v_fma_f32 v244, v244, s97, -v2
	v_fma_f32 v245, v245, s97, -v2
	v_fma_f32 v246, v246, s97, -v2
	v_fma_f32 v247, v247, s97, -v2
	v_fma_f32 v248, v248, s97, -v2
	v_fma_f32 v249, v249, s97, -v2
	v_fma_f32 v250, v250, s97, -v2
	v_mfma_f32_32x32x16_bf16 v[98:113], v[166:169], v[8:11], v[98:113]
	ds_read_b128 v[166:169], v203 offset:36864
	v_fma_f32 v251, v251, s97, -v2
	v_exp_f32_e32 v244, v244
	v_exp_f32_e32 v245, v245
	v_exp_f32_e32 v246, v246
	v_exp_f32_e32 v247, v247
	v_exp_f32_e32 v248, v248
	v_exp_f32_e32 v249, v249
	v_mfma_f32_32x32x16_bf16 v[66:81], v[170:173], v[8:11], v[66:81]
	ds_read_b128 v[170:173], v203 offset:40960
	v_exp_f32_e32 v250, v250
	v_exp_f32_e32 v251, v251
	v_add_f32_e32 v17, v244, v17
	v_add_f32_e32 v219, v245, v219
	v_add_f32_e32 v17, v246, v17
	v_add_f32_e32 v219, v247, v219
	v_add_f32_e32 v17, v248, v17
	v_mfma_f32_32x32x16_bf16 v[34:49], v[174:177], v[8:11], v[34:49]
	ds_read_b128 v[174:177], v203 offset:45056
	v_add_f32_e32 v219, v249, v219
	v_add_f32_e32 v17, v250, v17
	v_add_f32_e32 v219, v251, v219
	v_cvt_pk_bf16_f32 v244, v244, v245
	v_cvt_pk_bf16_f32 v245, v246, v247
	v_cvt_pk_bf16_f32 v246, v248, v249
	v_cvt_pk_bf16_f32 v247, v250, v251
	s_waitcnt lgkmcnt(3)
	v_mfma_f32_32x32x16_bf16 v[130:145], v[162:165], v[4:7], v[130:145]
	v_add_f32_e32 v17, v17, v219
	v_mfma_f32_32x32x16_bf16 v[114:129], v[162:165], v[244:247], v[114:129]
	s_waitcnt lgkmcnt(2)
	v_mfma_f32_32x32x16_bf16 v[98:113], v[166:169], v[4:7], v[98:113]
	v_add_f32_e32 v187, v187, v17
	v_mfma_f32_32x32x16_bf16 v[82:97], v[166:169], v[244:247], v[82:97]
	s_waitcnt lgkmcnt(1)
	v_mfma_f32_32x32x16_bf16 v[66:81], v[170:173], v[4:7], v[66:81]
	v_mfma_f32_32x32x16_bf16 v[50:65], v[170:173], v[244:247], v[50:65]
	s_waitcnt lgkmcnt(0)
	v_mfma_f32_32x32x16_bf16 v[34:49], v[174:177], v[4:7], v[34:49]
	v_mfma_f32_32x32x16_bf16 v[18:33], v[174:177], v[244:247], v[18:33]
